# four-step GEMM start stagger, step 3 sleeps in the QKV phase and 2 sleeps in the up-projection phase (with attention setprio)
# baseline (speedup 1.0000x reference)
; __global__ void __launch_bounds__(NWAVES * 64, 2) hymba_fwd(Args A) {
;     ...
;     {
;         pg8::Gemm g{(const pg8::bf16_t*)(ws + WS_XA), (const pg8::bf16_t*)(ws + WS_W1), M1, DIN, DM, DM};
;         pg8::StaticOrder S; S.init(M1, DIN, G, bx);
;         pg8::Epi1 E{(const float*)(ws + WS_RS1), (const float*)(ws + WS_ROPE), A.out, (pg8::bf16_t*)(ws + WS_QD), (pg8::bf16_t*)(ws + WS_QS), (pg8::bf16_t*)(ws + WS_KD), (pg8::bf16_t*)(ws + WS_KS),
;                     (pg8::bf16_t*)(ws + WS_VDT), (pg8::bf16_t*)(ws + WS_VST)};
;         pg8::gemm_phase<pg8::Epi1, pg8::StaticOrder, true, true>(lds, g, S, E);
.Lstag_p1_b:
	s_bitcmp1_b32 s22, 4
	s_cbranch_scc0 .Lstag_p1
	s_sleep 127
	s_sleep 127
	s_sleep 127
	s_sleep 127
	s_sleep 127
	s_sleep 127
